# compression MLP: ring-pipelined first matmul plus second matmul's 32 weight loads issued together
# speedup vs baseline: 1.0027x; 1.0027x over previous
.LBB0_550:
	v_ashrrev_i32_e32 v59, 1, v58
	v_add_u32_e32 v59, v59, v53
	v_lshl_add_u64 v[60:61], v[54:55], 0, s[8:9]
	s_mov_b32 s13, 0x4b80000
	v_min_i32_e32 v59, 0x1fff, v59
	v_add_co_u32_e32 v90, vcc, s13, v60
	v_add_u32_e32 v59, s3, v59
	s_nop 0
	v_addc_co_u32_e32 v91, vcc, 0, v61, vcc
	v_mad_i64_i32 v[106:107], s[30:31], v59, s23, v[56:57]
	s_mov_b32 s13, 0x4b90000
	v_add_co_u32_e64 v94, s[44:45], s13, v60
	s_mov_b32 s13, 0x4ba0000
	s_nop 0
	v_addc_co_u32_e64 v95, vcc, 0, v61, s[44:45]
	v_add_co_u32_e64 v96, s[46:47], s13, v60
	s_mov_b32 s13, 0x4bb0000
	s_nop 0
	v_addc_co_u32_e64 v97, vcc, 0, v61, s[46:47]
	v_add_co_u32_e64 v98, s[48:49], s13, v60
	s_mov_b32 s13, 0x4bc0000
	s_nop 0
	v_addc_co_u32_e64 v99, vcc, 0, v61, s[48:49]
	v_add_co_u32_e64 v100, s[50:51], s13, v60
	s_mov_b32 s13, 0x4bd0000
	s_nop 0
	v_addc_co_u32_e64 v101, vcc, 0, v61, s[50:51]
	v_add_co_u32_e64 v102, s[52:53], s13, v60
	s_mov_b32 s13, 0x4be0000
	s_nop 0
	v_addc_co_u32_e64 v103, vcc, 0, v61, s[52:53]
	v_add_co_u32_e64 v104, s[54:55], s13, v60
	s_mov_b32 s13, 0x4bf0000
	s_nop 0
	v_addc_co_u32_e64 v105, vcc, 0, v61, s[54:55]
	v_add_co_u32_e64 v60, s[56:57], s13, v60
	s_nop 0
	v_addc_co_u32_e64 v61, vcc, 0, v61, s[56:57]
	v_add_u32_e32 v59, 2, v72
	v_ashrrev_i32_e32 v59, 1, v59
	v_add_u32_e32 v59, v59, v53
	v_min_i32_e32 v59, 0x1fff, v59
	v_add_u32_e32 v59, s3, v59
	v_mad_i64_i32 v[172:173], s[30:31], v59, s23, v[56:57]
	v_add_u32_e32 v59, 4, v72
	v_ashrrev_i32_e32 v59, 1, v59
	v_add_u32_e32 v59, v59, v53
	v_min_i32_e32 v59, 0x1fff, v59
	v_add_u32_e32 v59, s3, v59
	v_mad_i64_i32 v[154:155], s[30:31], v59, s23, v[56:57]
	v_add_u32_e32 v59, 6, v72
	v_ashrrev_i32_e32 v59, 1, v59
	v_add_u32_e32 v59, v59, v53
	v_min_i32_e32 v59, 0x1fff, v59
	v_add_u32_e32 v59, s3, v59
	v_mad_i64_i32 v[116:117], s[30:31], v59, s23, v[56:57]
	global_load_dwordx4 v[212:215], v[106:107], off
	global_load_dwordx4 v[216:219], v[90:91], off
	global_load_dwordx4 v[220:223], v[94:95], off
	global_load_dwordx4 v[224:227], v[96:97], off
	global_load_dwordx4 v[228:231], v[98:99], off
	global_load_dwordx4 v[232:235], v[100:101], off
	global_load_dwordx4 v[236:239], v[102:103], off
	global_load_dwordx4 v[240:243], v[104:105], off
	global_load_dwordx4 v[244:247], v[60:61], off
	global_load_dwordx4 v[248:251], v[106:107], off offset:64
	global_load_dwordx4 v[138:141], v[90:91], off offset:64
	global_load_dwordx4 v[142:145], v[94:95], off offset:64
	global_load_dwordx4 v[146:149], v[96:97], off offset:64
	global_load_dwordx4 v[150:153], v[98:99], off offset:64
	global_load_dwordx4 v[176:179], v[100:101], off offset:64
	global_load_dwordx4 v[180:183], v[102:103], off offset:64
	global_load_dwordx4 v[184:187], v[104:105], off offset:64
	global_load_dwordx4 v[164:167], v[60:61], off offset:64
	global_load_dwordx4 v[168:171], v[172:173], off
	global_load_dwordx4 v[108:111], v[90:91], off offset:128
	global_load_dwordx4 v[112:115], v[94:95], off offset:128
	global_load_dwordx4 v[82:85], v[96:97], off offset:128
	global_load_dwordx4 v[86:89], v[98:99], off offset:128
	s_waitcnt vmcnt(21)
	v_mfma_f32_16x16x32_bf16 v[2:5], v[212:215], v[216:219], v[2:5]
	global_load_dwordx4 v[216:219], v[100:101], off offset:128
	s_waitcnt vmcnt(21)
	v_mfma_f32_16x16x32_bf16 v[6:9], v[212:215], v[220:223], v[6:9]
	global_load_dwordx4 v[220:223], v[102:103], off offset:128
	s_waitcnt vmcnt(21)
	v_mfma_f32_16x16x32_bf16 v[10:13], v[212:215], v[224:227], v[10:13]
	global_load_dwordx4 v[224:227], v[104:105], off offset:128
	s_waitcnt vmcnt(21)
	v_mfma_f32_16x16x32_bf16 v[14:17], v[212:215], v[228:231], v[14:17]
	global_load_dwordx4 v[228:231], v[60:61], off offset:128
	s_waitcnt vmcnt(21)
	v_mfma_f32_16x16x32_bf16 v[18:21], v[212:215], v[232:235], v[18:21]
	global_load_dwordx4 v[232:235], v[172:173], off offset:64
	s_waitcnt vmcnt(21)
	v_mfma_f32_16x16x32_bf16 v[22:25], v[212:215], v[236:239], v[22:25]
	global_load_dwordx4 v[236:239], v[90:91], off offset:192
	s_waitcnt vmcnt(21)
	v_mfma_f32_16x16x32_bf16 v[26:29], v[212:215], v[240:243], v[26:29]
	global_load_dwordx4 v[240:243], v[94:95], off offset:192
	s_waitcnt vmcnt(21)
	v_mfma_f32_16x16x32_bf16 v[30:33], v[212:215], v[244:247], v[30:33]
	global_load_dwordx4 v[244:247], v[96:97], off offset:192
	global_load_dwordx4 v[212:215], v[98:99], off offset:192
	s_waitcnt vmcnt(21)
	v_mfma_f32_16x16x32_bf16 v[2:5], v[248:251], v[138:141], v[2:5]
	global_load_dwordx4 v[138:141], v[100:101], off offset:192
	s_waitcnt vmcnt(21)
	v_mfma_f32_16x16x32_bf16 v[6:9], v[248:251], v[142:145], v[6:9]
	global_load_dwordx4 v[142:145], v[102:103], off offset:192
	s_waitcnt vmcnt(21)
	v_mfma_f32_16x16x32_bf16 v[10:13], v[248:251], v[146:149], v[10:13]
	global_load_dwordx4 v[146:149], v[104:105], off offset:192
	s_waitcnt vmcnt(21)
	v_mfma_f32_16x16x32_bf16 v[14:17], v[248:251], v[150:153], v[14:17]
	global_load_dwordx4 v[150:153], v[60:61], off offset:192
	s_waitcnt vmcnt(21)
	v_mfma_f32_16x16x32_bf16 v[18:21], v[248:251], v[176:179], v[18:21]
	global_load_dwordx4 v[176:179], v[154:155], off
	s_waitcnt vmcnt(21)
	v_mfma_f32_16x16x32_bf16 v[22:25], v[248:251], v[180:183], v[22:25]
	global_load_dwordx4 v[180:183], v[90:91], off offset:256
	s_waitcnt vmcnt(21)
	v_mfma_f32_16x16x32_bf16 v[26:29], v[248:251], v[184:187], v[26:29]
	global_load_dwordx4 v[184:187], v[94:95], off offset:256
	s_waitcnt vmcnt(21)
	v_mfma_f32_16x16x32_bf16 v[30:33], v[248:251], v[164:167], v[30:33]
	global_load_dwordx4 v[164:167], v[96:97], off offset:256
	global_load_dwordx4 v[248:251], v[98:99], off offset:256
	s_waitcnt vmcnt(21)
	v_mfma_f32_16x16x32_bf16 v[2:5], v[168:171], v[108:111], v[2:5]
	global_load_dwordx4 v[108:111], v[100:101], off offset:256
	s_waitcnt vmcnt(21)
	v_mfma_f32_16x16x32_bf16 v[6:9], v[168:171], v[112:115], v[6:9]
	global_load_dwordx4 v[112:115], v[102:103], off offset:256
	s_waitcnt vmcnt(21)
	v_mfma_f32_16x16x32_bf16 v[10:13], v[168:171], v[82:85], v[10:13]
	global_load_dwordx4 v[82:85], v[104:105], off offset:256
	s_waitcnt vmcnt(21)
	v_mfma_f32_16x16x32_bf16 v[14:17], v[168:171], v[86:89], v[14:17]
	global_load_dwordx4 v[86:89], v[60:61], off offset:256
	s_waitcnt vmcnt(21)
	v_mfma_f32_16x16x32_bf16 v[18:21], v[168:171], v[216:219], v[18:21]
	global_load_dwordx4 v[216:219], v[154:155], off offset:64
	s_waitcnt vmcnt(21)
	v_mfma_f32_16x16x32_bf16 v[22:25], v[168:171], v[220:223], v[22:25]
	global_load_dwordx4 v[220:223], v[90:91], off offset:320
	s_waitcnt vmcnt(21)
	v_mfma_f32_16x16x32_bf16 v[26:29], v[168:171], v[224:227], v[26:29]
	global_load_dwordx4 v[224:227], v[94:95], off offset:320
	s_waitcnt vmcnt(21)
	v_mfma_f32_16x16x32_bf16 v[30:33], v[168:171], v[228:231], v[30:33]
	global_load_dwordx4 v[228:231], v[96:97], off offset:320
	global_load_dwordx4 v[168:171], v[98:99], off offset:320
	s_waitcnt vmcnt(21)
	v_mfma_f32_16x16x32_bf16 v[2:5], v[232:235], v[236:239], v[2:5]
	global_load_dwordx4 v[236:239], v[100:101], off offset:320
	s_waitcnt vmcnt(21)
	v_mfma_f32_16x16x32_bf16 v[6:9], v[232:235], v[240:243], v[6:9]
	global_load_dwordx4 v[240:243], v[102:103], off offset:320
	s_waitcnt vmcnt(21)
	v_mfma_f32_16x16x32_bf16 v[10:13], v[232:235], v[244:247], v[10:13]
	global_load_dwordx4 v[244:247], v[104:105], off offset:320
	s_waitcnt vmcnt(21)
	v_mfma_f32_16x16x32_bf16 v[14:17], v[232:235], v[212:215], v[14:17]
	global_load_dwordx4 v[212:215], v[60:61], off offset:320
	s_waitcnt vmcnt(21)
	v_mfma_f32_16x16x32_bf16 v[18:21], v[232:235], v[138:141], v[18:21]
	global_load_dwordx4 v[138:141], v[116:117], off
	s_waitcnt vmcnt(21)
	v_mfma_f32_16x16x32_bf16 v[22:25], v[232:235], v[142:145], v[22:25]
	global_load_dwordx4 v[142:145], v[90:91], off offset:384
	s_waitcnt vmcnt(21)
	v_mfma_f32_16x16x32_bf16 v[26:29], v[232:235], v[146:149], v[26:29]
	global_load_dwordx4 v[146:149], v[94:95], off offset:384
	s_waitcnt vmcnt(21)
	v_mfma_f32_16x16x32_bf16 v[30:33], v[232:235], v[150:153], v[30:33]
	global_load_dwordx4 v[150:153], v[96:97], off offset:384
	global_load_dwordx4 v[232:235], v[98:99], off offset:384
	s_waitcnt vmcnt(21)
	v_mfma_f32_16x16x32_bf16 v[2:5], v[176:179], v[180:183], v[2:5]
	global_load_dwordx4 v[180:183], v[100:101], off offset:384
	s_waitcnt vmcnt(21)
	v_mfma_f32_16x16x32_bf16 v[6:9], v[176:179], v[184:187], v[6:9]
	global_load_dwordx4 v[184:187], v[102:103], off offset:384
	s_waitcnt vmcnt(21)
	v_mfma_f32_16x16x32_bf16 v[10:13], v[176:179], v[164:167], v[10:13]
	global_load_dwordx4 v[164:167], v[104:105], off offset:384
	s_waitcnt vmcnt(21)
	v_mfma_f32_16x16x32_bf16 v[14:17], v[176:179], v[248:251], v[14:17]
	global_load_dwordx4 v[248:251], v[60:61], off offset:384
	s_waitcnt vmcnt(21)
	v_mfma_f32_16x16x32_bf16 v[18:21], v[176:179], v[108:111], v[18:21]
	global_load_dwordx4 v[108:111], v[116:117], off offset:64
	s_waitcnt vmcnt(21)
	v_mfma_f32_16x16x32_bf16 v[22:25], v[176:179], v[112:115], v[22:25]
	global_load_dwordx4 v[112:115], v[90:91], off offset:448
	s_waitcnt vmcnt(21)
	v_mfma_f32_16x16x32_bf16 v[26:29], v[176:179], v[82:85], v[26:29]
	global_load_dwordx4 v[82:85], v[94:95], off offset:448
	s_waitcnt vmcnt(21)
	v_mfma_f32_16x16x32_bf16 v[30:33], v[176:179], v[86:89], v[30:33]
	global_load_dwordx4 v[86:89], v[96:97], off offset:448
	global_load_dwordx4 v[176:179], v[98:99], off offset:448
	s_waitcnt vmcnt(21)
	v_mfma_f32_16x16x32_bf16 v[2:5], v[216:219], v[220:223], v[2:5]
	global_load_dwordx4 v[220:223], v[100:101], off offset:448
	s_waitcnt vmcnt(21)
	v_mfma_f32_16x16x32_bf16 v[6:9], v[216:219], v[224:227], v[6:9]
	global_load_dwordx4 v[224:227], v[102:103], off offset:448
	s_waitcnt vmcnt(21)
	v_mfma_f32_16x16x32_bf16 v[10:13], v[216:219], v[228:231], v[10:13]
	global_load_dwordx4 v[228:231], v[104:105], off offset:448
	s_waitcnt vmcnt(21)
	v_mfma_f32_16x16x32_bf16 v[14:17], v[216:219], v[168:171], v[14:17]
	global_load_dwordx4 v[168:171], v[60:61], off offset:448
	s_waitcnt vmcnt(21)
	v_mfma_f32_16x16x32_bf16 v[18:21], v[216:219], v[236:239], v[18:21]
	s_waitcnt vmcnt(20)
	v_mfma_f32_16x16x32_bf16 v[22:25], v[216:219], v[240:243], v[22:25]
	s_waitcnt vmcnt(19)
	v_mfma_f32_16x16x32_bf16 v[26:29], v[216:219], v[244:247], v[26:29]
	s_waitcnt vmcnt(18)
	v_mfma_f32_16x16x32_bf16 v[30:33], v[216:219], v[212:215], v[30:33]
	s_waitcnt vmcnt(16)
	v_mfma_f32_16x16x32_bf16 v[2:5], v[138:141], v[142:145], v[2:5]
	s_waitcnt vmcnt(15)
	v_mfma_f32_16x16x32_bf16 v[6:9], v[138:141], v[146:149], v[6:9]
	s_waitcnt vmcnt(14)
	v_mfma_f32_16x16x32_bf16 v[10:13], v[138:141], v[150:153], v[10:13]
	s_waitcnt vmcnt(13)
	v_mfma_f32_16x16x32_bf16 v[14:17], v[138:141], v[232:235], v[14:17]
	s_waitcnt vmcnt(12)
	v_mfma_f32_16x16x32_bf16 v[18:21], v[138:141], v[180:183], v[18:21]
	s_waitcnt vmcnt(11)
	v_mfma_f32_16x16x32_bf16 v[22:25], v[138:141], v[184:187], v[22:25]
	s_waitcnt vmcnt(10)
	v_mfma_f32_16x16x32_bf16 v[26:29], v[138:141], v[164:167], v[26:29]
	s_waitcnt vmcnt(9)
	v_mfma_f32_16x16x32_bf16 v[30:33], v[138:141], v[248:251], v[30:33]
	s_waitcnt vmcnt(7)
	v_mfma_f32_16x16x32_bf16 v[2:5], v[108:111], v[112:115], v[2:5]
	s_waitcnt vmcnt(6)
	v_mfma_f32_16x16x32_bf16 v[6:9], v[108:111], v[82:85], v[6:9]
	s_waitcnt vmcnt(5)
	v_mfma_f32_16x16x32_bf16 v[10:13], v[108:111], v[86:89], v[10:13]
	s_waitcnt vmcnt(4)
	v_mfma_f32_16x16x32_bf16 v[14:17], v[108:111], v[176:179], v[14:17]
	s_waitcnt vmcnt(3)
	v_mfma_f32_16x16x32_bf16 v[18:21], v[108:111], v[220:223], v[18:21]
	s_waitcnt vmcnt(2)
	v_mfma_f32_16x16x32_bf16 v[22:25], v[108:111], v[224:227], v[22:25]
	s_waitcnt vmcnt(1)
	v_mfma_f32_16x16x32_bf16 v[26:29], v[108:111], v[228:231], v[26:29]
	s_waitcnt vmcnt(0)
	v_mfma_f32_16x16x32_bf16 v[30:33], v[108:111], v[168:171], v[30:33]
	v_add_u32_e32 v53, 0x4000, v79
	ds_write2_b32 v53, v2, v6 offset1:16
	ds_write2_b32 v53, v3, v7 offset0:132 offset1:148
	v_add_u32_e32 v2, 0x4400, v79
	ds_write2_b32 v2, v4, v8 offset0:8 offset1:24
	ds_write2_b32 v2, v5, v9 offset0:140 offset1:156
	ds_write2_b32 v53, v10, v14 offset0:32 offset1:48
	ds_write2_b32 v53, v11, v15 offset0:164 offset1:180
	ds_write2_b32 v2, v12, v16 offset0:40 offset1:56
	ds_write2_b32 v2, v13, v17 offset0:172 offset1:188
	ds_write2_b32 v53, v18, v22 offset0:64 offset1:80
	ds_write2_b32 v53, v19, v23 offset0:196 offset1:212
	ds_write2_b32 v2, v20, v24 offset0:72 offset1:88
	ds_write2_b32 v2, v21, v25 offset0:204 offset1:220
	ds_write2_b32 v53, v26, v30 offset0:96 offset1:112
	ds_write2_b32 v53, v27, v31 offset0:228 offset1:244
	ds_write2_b32 v2, v28, v32 offset0:104 offset1:120
	ds_write2_b32 v2, v29, v33 offset0:236 offset1:252
	s_waitcnt lgkmcnt(0)
	s_barrier
	ds_read_b128 v[2:5], v74 offset:16384
	s_movk_i32 s8, 0x7fff
	s_waitcnt lgkmcnt(0)
	v_pk_add_f32 v[6:7], v[4:5], 0 op_sel_hi:[1,0]
	v_pk_add_f32 v[8:9], v[2:3], 0 op_sel_hi:[1,0]
	ds_read_b128 v[2:5], v74 offset:24832
	s_waitcnt lgkmcnt(0)
	v_pk_add_f32 v[6:7], v[6:7], v[4:5]
	v_pk_add_f32 v[8:9], v[8:9], v[2:3]
	ds_read_b128 v[2:5], v74 offset:33280
	s_waitcnt lgkmcnt(0)
	v_pk_add_f32 v[6:7], v[6:7], v[4:5]
	v_pk_add_f32 v[8:9], v[8:9], v[2:3]
	ds_read_b128 v[2:5], v74 offset:41728
	s_waitcnt lgkmcnt(0)
	v_pk_add_f32 v[6:7], v[6:7], v[4:5]
	v_pk_add_f32 v[8:9], v[8:9], v[2:3]
	ds_read_b128 v[2:5], v74 offset:50176
	s_waitcnt lgkmcnt(0)
	v_pk_add_f32 v[6:7], v[6:7], v[4:5]
	v_pk_add_f32 v[8:9], v[8:9], v[2:3]
	ds_read_b128 v[2:5], v74 offset:58624
	s_waitcnt lgkmcnt(0)
	v_pk_add_f32 v[6:7], v[6:7], v[4:5]
	v_pk_add_f32 v[8:9], v[8:9], v[2:3]
	ds_read_b128 v[2:5], v75 offset:50688
	s_waitcnt lgkmcnt(0)
	v_pk_add_f32 v[6:7], v[6:7], v[4:5]
	v_pk_add_f32 v[8:9], v[8:9], v[2:3]
	ds_read_b128 v[2:5], v75 offset:59136
	s_waitcnt lgkmcnt(0)
	v_pk_add_f32 v[8:9], v[8:9], v[2:3]
	v_or_b32_e32 v2, s2, v73
	v_ashrrev_i32_e32 v3, 31, v2
	v_lshl_add_u64 v[2:3], v[2:3], 2, s[14:15]
	v_pk_add_f32 v[6:7], v[6:7], v[4:5]
	global_load_dwordx4 v[2:5], v[2:3], off
	s_waitcnt vmcnt(0)
	v_mov_b32_e32 v10, v3
	v_mov_b32_e32 v11, v4
	v_mov_b32_e32 v3, v5
	v_mov_b32_e32 v5, v7
	v_pk_mov_b32 v[6:7], v[8:9], v[6:7] op_sel:[1,0]
	v_mov_b32_e32 v4, v8
	v_pk_add_f32 v[6:7], v[6:7], v[10:11]
	v_pk_add_f32 v[2:3], v[2:3], v[4:5]
	v_mul_f32_e32 v5, 0x3d372713, v6
	v_mul_f32_e32 v5, v6, v5
	v_fma_f32 v5, v6, v5, v6
	v_mul_f32_e32 v5, 0x3f4c422a, v5
	v_add_f32_e32 v5, v5, v5
	v_mul_f32_e32 v5, 0x3fb8aa3b, v5
	v_exp_f32_e32 v8, v5
	v_mul_f32_e32 v5, 0x3d372713, v7
	v_mul_f32_e32 v5, v7, v5
	v_fma_f32 v5, v7, v5, v7
	v_mul_f32_e32 v5, 0x3f4c422a, v5
	v_add_f32_e32 v5, v5, v5
	v_mul_f32_e32 v5, 0x3fb8aa3b, v5
	v_exp_f32_e32 v9, v5
	v_pk_mul_f32 v[6:7], v[6:7], 0.5 op_sel_hi:[1,0]
	v_mul_f32_e32 v4, 0x3d372713, v2
	v_mul_f32_e32 v4, v2, v4
	v_pk_add_f32 v[8:9], v[8:9], 1.0 op_sel_hi:[1,0]
	v_fma_f32 v4, v2, v4, v2
	v_div_scale_f32 v5, s[2:3], v9, v9, 2.0
	v_rcp_f32_e32 v10, v5
	v_mul_f32_e32 v4, 0x3f4c422a, v4
	v_add_f32_e32 v4, v4, v4
	v_mul_f32_e32 v4, 0x3fb8aa3b, v4
	v_fma_f32 v11, -v5, v10, 1.0
	v_fmac_f32_e32 v10, v11, v10
	v_div_scale_f32 v11, vcc, 2.0, v9, 2.0
	v_mul_f32_e32 v12, v11, v10
	v_fma_f32 v13, -v5, v12, v11
	v_fmac_f32_e32 v12, v13, v10
	v_fma_f32 v5, -v5, v12, v11
	v_div_fmas_f32 v5, v5, v10, v12
	v_div_fixup_f32 v9, v5, v9, 2.0
	v_div_scale_f32 v5, s[2:3], v8, v8, 2.0
	v_rcp_f32_e32 v10, v5
	v_exp_f32_e32 v4, v4
	v_fma_f32 v11, -v5, v10, 1.0
	v_fmac_f32_e32 v10, v11, v10
	v_div_scale_f32 v11, vcc, 2.0, v8, 2.0
	v_mul_f32_e32 v12, v11, v10
	v_fma_f32 v13, -v5, v12, v11
	v_fmac_f32_e32 v12, v13, v10
	v_fma_f32 v5, -v5, v12, v11
	v_div_fmas_f32 v5, v5, v10, v12
	v_div_fixup_f32 v8, v5, v8, 2.0
	v_pk_add_f32 v[8:9], v[8:9], 1.0 op_sel_hi:[1,0] neg_lo:[1,0] neg_hi:[1,0]
	s_nop 0
	v_pk_add_f32 v[8:9], v[8:9], 1.0 op_sel_hi:[1,0]
	s_nop 0
	v_pk_mul_f32 v[6:7], v[6:7], v[8:9]
	s_nop 0
	v_and_b32_sdwa v5, v7, v194 dst_sel:DWORD dst_unused:UNUSED_PAD src0_sel:WORD_1 src1_sel:DWORD
	v_and_b32_sdwa v8, v6, v194 dst_sel:DWORD dst_unused:UNUSED_PAD src0_sel:WORD_1 src1_sel:DWORD
	v_add3_u32 v7, v7, v5, s8
	v_add3_u32 v5, v6, v8, s8
	v_and_b32_e32 v6, 0xffff0000, v5
	v_mul_f32_e32 v5, 0x3d372713, v3
	v_mul_f32_e32 v5, v3, v5
	v_fma_f32 v5, v3, v5, v3
	v_mul_f32_e32 v5, 0x3f4c422a, v5
	v_add_f32_e32 v5, v5, v5
	v_mul_f32_e32 v5, 0x3fb8aa3b, v5
	v_exp_f32_e32 v5, v5
	v_pk_mul_f32 v[2:3], v[2:3], 0.5 op_sel_hi:[1,0]
	v_pk_add_f32 v[4:5], v[4:5], 1.0 op_sel_hi:[1,0]
	s_nop 0
	v_div_scale_f32 v8, s[2:3], v5, v5, 2.0
	v_rcp_f32_e32 v9, v8
	s_nop 0
	v_fma_f32 v10, -v8, v9, 1.0
	v_fmac_f32_e32 v9, v10, v9
	v_div_scale_f32 v10, vcc, 2.0, v5, 2.0
	v_mul_f32_e32 v11, v10, v9
	v_fma_f32 v12, -v8, v11, v10
	v_fmac_f32_e32 v11, v12, v9
	v_fma_f32 v8, -v8, v11, v10
	v_div_fmas_f32 v8, v8, v9, v11
	v_div_fixup_f32 v5, v8, v5, 2.0
	v_div_scale_f32 v8, s[2:3], v4, v4, 2.0
	v_rcp_f32_e32 v9, v8
	s_nop 0
	v_fma_f32 v10, -v8, v9, 1.0
	v_fmac_f32_e32 v9, v10, v9
	v_div_scale_f32 v10, vcc, 2.0, v4, 2.0
	v_mul_f32_e32 v11, v10, v9
	v_fma_f32 v12, -v8, v11, v10
	v_fmac_f32_e32 v11, v12, v9
	v_fma_f32 v8, -v8, v11, v10
	v_div_fmas_f32 v8, v8, v9, v11
	v_div_fixup_f32 v4, v8, v4, 2.0
	v_pk_add_f32 v[4:5], v[4:5], 1.0 op_sel_hi:[1,0] neg_lo:[1,0] neg_hi:[1,0]
	s_nop 0
	v_pk_add_f32 v[4:5], v[4:5], 1.0 op_sel_hi:[1,0]
	s_nop 0
	v_pk_mul_f32 v[2:3], v[2:3], v[4:5]
	s_nop 0
	v_and_b32_sdwa v4, v3, v194 dst_sel:DWORD dst_unused:UNUSED_PAD src0_sel:WORD_1 src1_sel:DWORD
	v_and_b32_sdwa v5, v2, v194 dst_sel:DWORD dst_unused:UNUSED_PAD src0_sel:WORD_1 src1_sel:DWORD
	v_add3_u32 v3, v3, v4, s8
	v_add3_u32 v2, v2, v5, s8
	v_and_b32_e32 v3, 0xffff0000, v3
	v_or_b32_sdwa v3, v3, v7 dst_sel:DWORD dst_unused:UNUSED_PAD src0_sel:DWORD src1_sel:WORD_1
	v_or_b32_sdwa v2, v2, v6 dst_sel:DWORD dst_unused:UNUSED_PAD src0_sel:WORD_1 src1_sel:DWORD
	ds_write_b64 v76, v[2:3]
	s_waitcnt lgkmcnt(0)
	s_barrier
	s_and_saveexec_b64 s[2:3], s[34:35]
	s_cbranch_execz .LBB0_553
	s_ashr_i32 s8, s16, 7
	s_ashr_i32 s9, s8, 31
	s_lshl_b64 s[8:9], s[8:9], 15
	v_lshl_add_u64 v[14:15], v[48:49], 0, s[8:9]
	global_load_dword v212, v[14:15], off
	global_load_dword v213, v[14:15], off offset:256
	global_load_dword v214, v[14:15], off offset:512
	global_load_dword v215, v[14:15], off offset:768
	global_load_dword v216, v[14:15], off offset:1024
	global_load_dword v217, v[14:15], off offset:1280
	global_load_dword v218, v[14:15], off offset:1536
	global_load_dword v219, v[14:15], off offset:1792
	s_movk_i32 s8, 0x2000
	v_add_co_u32_e32 v10, vcc, s8, v14
	s_nop 1
	v_addc_co_u32_e32 v11, vcc, 0, v15, vcc
	global_load_dword v220, v[10:11], off
	global_load_dword v221, v[10:11], off offset:256
	global_load_dword v222, v[10:11], off offset:512
	global_load_dword v223, v[10:11], off offset:768
	global_load_dword v224, v[10:11], off offset:1024
	global_load_dword v225, v[10:11], off offset:1280
	global_load_dword v226, v[10:11], off offset:1536
	global_load_dword v227, v[10:11], off offset:1792
	s_movk_i32 s8, 0x4000
	v_add_co_u32_e32 v10, vcc, s8, v14
	s_nop 1
	v_addc_co_u32_e32 v11, vcc, 0, v15, vcc
	global_load_dword v228, v[10:11], off
	global_load_dword v229, v[10:11], off offset:256
	global_load_dword v230, v[10:11], off offset:512
	global_load_dword v231, v[10:11], off offset:768
	global_load_dword v232, v[10:11], off offset:1024
	global_load_dword v233, v[10:11], off offset:1280
	global_load_dword v234, v[10:11], off offset:1536
	global_load_dword v235, v[10:11], off offset:1792
	s_movk_i32 s8, 0x6000
	v_add_co_u32_e32 v10, vcc, s8, v14
	s_nop 1
	v_addc_co_u32_e32 v11, vcc, 0, v15, vcc
	global_load_dword v236, v[10:11], off
	global_load_dword v237, v[10:11], off offset:256
	global_load_dword v238, v[10:11], off offset:512
	global_load_dword v239, v[10:11], off offset:768
	global_load_dword v240, v[10:11], off offset:1024
	global_load_dword v241, v[10:11], off offset:1280
	global_load_dword v242, v[10:11], off offset:1536
	global_load_dword v243, v[10:11], off offset:1792
	ds_read_b128 v[244:247], v77
	ds_read_b128 v[248:251], v77 offset:64
	ds_read_b128 v[138:141], v77 offset:128
	ds_read_b128 v[142:145], v77 offset:192
	s_waitcnt vmcnt(0) lgkmcnt(0)
	v_cvt_pk_bf16_f32 v6, v212, v213
	v_cvt_pk_bf16_f32 v7, v214, v215
	v_cvt_pk_bf16_f32 v8, v216, v217
	v_cvt_pk_bf16_f32 v9, v218, v219
	v_cvt_pk_bf16_f32 v10, v220, v221
	v_cvt_pk_bf16_f32 v11, v222, v223
	v_cvt_pk_bf16_f32 v12, v224, v225
	v_cvt_pk_bf16_f32 v13, v226, v227
	v_cvt_pk_bf16_f32 v16, v228, v229
	v_cvt_pk_bf16_f32 v17, v230, v231
	v_cvt_pk_bf16_f32 v18, v232, v233
	v_cvt_pk_bf16_f32 v19, v234, v235
	v_cvt_pk_bf16_f32 v20, v236, v237
	v_cvt_pk_bf16_f32 v21, v238, v239
	v_cvt_pk_bf16_f32 v22, v240, v241
	v_cvt_pk_bf16_f32 v23, v242, v243
	s_nop 1
	v_mfma_f32_16x16x32_bf16 v[2:5], v[244:247], v[6:9], 0
	v_mfma_f32_16x16x32_bf16 v[2:5], v[248:251], v[10:13], v[2:5]
	v_mfma_f32_16x16x32_bf16 v[2:5], v[138:141], v[16:19], v[2:5]
	v_mfma_f32_16x16x32_bf16 v[2:5], v[142:145], v[20:23], v[2:5]
	v_add_u32_e32 v6, 0x2000, v80
	s_nop 6
	ds_write2_b32 v6, v2, v3 offset1:65
	ds_write2_b32 v6, v4, v5 offset0:130 offset1:195
